# expert up-projection weight conversion in phase 1 is software pipelined (next trip loads issued before the LDS transpose of the current one) with non-temporal source loads
# speedup vs baseline: 1.0132x; 1.0031x over previous
; #define LAS __attribute__((address_space(3)))
; __device__ __forceinline__ unsigned cvt_pk_bf16(float lo, float hi) { unsigned r; asm("v_cvt_pk_bf16_f32 %0, %1, %2" : "=v"(r) : "v"(lo), "v"(hi)); return r; }
;     const int tid = fresh_tid();
;     const int tk = K / 64, tn = (N + 63) / 64, per = tk * tn, total = batch * per;
;     for (int gi = bid; gi * 4 < total; gi += nb) {
;         f32x4 v[4][2];
; #pragma unroll
;         for (int q = 0; q < 4; ++q) { const int it = gi * 4 + q;
;             v[q][0] = (f32x4){0.f, 0.f, 0.f, 0.f}; v[q][1] = (f32x4){0.f, 0.f, 0.f, 0.f};
;             if (it < total) { const int b = it / per, r = it % per, k0 = (r / tn) * 64, n0 = (r % tn) * 64;
;                 const float* sp = src + (size_t)b * sbs + (size_t)k0 * N + n0; const int c4 = (tid & 15) * 4;
;                 if (n0 + c4 < N) { v[q][0] = *(const f32x4*)(sp + (size_t)(tid >> 4) * N + c4); v[q][1] = *(const f32x4*)(sp + (size_t)((tid >> 4) + 32) * N + c4); } } }
; #pragma unroll
;         for (int q = 0; q < 4; ++q)
; #pragma unroll
;             for (int j = 0; j < 2; ++j) { const int row = (tid >> 4) + 32 * j, c4 = (tid & 15) * 4; LAS float* tp = tile + q * (64 * 65) + row * 65 + c4;
;                 tp[0] = v[q][j][0]; tp[1] = v[q][j][1]; tp[2] = v[q][j][2]; tp[3] = v[q][j][3]; }
;         __syncthreads();
; #pragma unroll
;         for (int q = 0; q < 4; ++q) { const int it = gi * 4 + q;
;             if (it < total) { const int b = it / per, r = it % per, k0 = (r / tn) * 64, n0 = (r % tn) * 64;
;                 const int n = tid >> 3, kc = (tid & 7) * 8;
;                 if (n0 + n < N) { float f[8];
; #pragma unroll
;                     for (int j = 0; j < 8; ++j) f[j] = tile[q * (64 * 65) + (kc + j) * 65 + n];
;                     u32x4 w; w.x = cvt_pk_bf16(f[0], f[1]); w.y = cvt_pk_bf16(f[2], f[3]); w.z = cvt_pk_bf16(f[4], f[5]); w.w = cvt_pk_bf16(f[6], f[7]);
;                     int nd = n0 + n + nshift; if (nd >= N) nd -= N;
;                     *(u32x4*)(dst + (size_t)b * dbs + (size_t)nd * ldd + kofs + k0 + kc) = w; } } }
;         __syncthreads();
;     }
; __device__ void phase_convert(const Params& p, LAS unsigned char* lds) {
;     ...
;     cvt_job(tile, p.ewu, (bf16_t*)(ws + WS_WU), NL * NE, 1024, FF, 1024, 0, (size_t)1024 * FF, (size_t)FF * 1024, (int)blockIdx.x, (int)gridDim.x);
.LBB0_698:
	v_readlane_b32 s6, v253, 34
	v_readlane_b32 s7, v253, 35
	v_mov_b32_e32 v0, v213
	s_andn2_b64 vcc, exec, s[6:7]
	s_cbranch_vccnz .LBB0_729
	v_lshrrev_b32_e32 v96, 4, v213
	v_and_b32_e32 v97, 15, v213
	v_lshlrev_b32_e32 v97, 4, v97
	v_mul_u32_u24_e32 v98, 0x2000, v96
	v_add_u32_e32 v98, v98, v97
	v_add_u32_e32 v99, 0x40000, v98
	v_lshrrev_b32_e32 v100, 3, v213
	v_and_b32_e32 v101, 7, v213
	v_lshlrev_b32_e32 v102, 4, v101
	v_mul_u32_u24_e32 v103, 0x800, v100
	v_add_u32_e32 v103, v103, v102
	v_mul_u32_u24_e32 v104, 0x104, v96
	v_add_u32_e32 v104, v104, v97
	v_mul_u32_u24_e32 v105, 0x820, v101
	v_lshl_add_u32 v105, v100, 2, v105
	v_mov_b32_e32 v80, v104
	v_mov_b32_e32 v88, v105
	v_add_u32_e32 v81, 0x2080, v104
	v_add_u32_e32 v89, 0x400, v105
	v_add_u32_e32 v82, 0x4100, v104
	v_add_u32_e32 v90, 0x4100, v105
	v_add_u32_e32 v83, 0x6180, v104
	v_add_u32_e32 v91, 0x4500, v105
	v_add_u32_e32 v84, 0x8200, v104
	v_add_u32_e32 v92, 0x8200, v105
	v_add_u32_e32 v85, 0xa280, v104
	v_add_u32_e32 v93, 0x8600, v105
	v_add_u32_e32 v86, 0xc300, v104
	v_add_u32_e32 v94, 0xc300, v105
	v_add_u32_e32 v87, 0xe380, v104
	v_add_u32_e32 v95, 0xc700, v105
	v_readlane_b32 s12, v252, 54
	v_readlane_b32 s13, v252, 55
	v_readlane_b32 s14, v253, 32
	v_readlane_b32 s15, v253, 33
	s_mov_b32 s20, s58
	s_lshr_b32 s16, s20, 7
	s_lshl_b32 s16, s16, 23
	s_bfe_u32 s17, s20, 0x40003
	s_lshl_b32 s17, s17, 19
	s_add_u32 s16, s16, s17
	s_and_b32 s17, s20, 7
	s_lshl_b32 s17, s17, 10
	s_add_u32 s16, s16, s17
	s_add_u32 s6, s12, s16
	s_addc_u32 s7, s13, 0
	global_load_dwordx4 v[0:3], v98, s[6:7] nt
	global_load_dwordx4 v[4:7], v99, s[6:7] nt
	global_load_dwordx4 v[8:11], v98, s[6:7] offset:256 nt
	global_load_dwordx4 v[12:15], v99, s[6:7] offset:256 nt
	global_load_dwordx4 v[16:19], v98, s[6:7] offset:512 nt
	global_load_dwordx4 v[20:23], v99, s[6:7] offset:512 nt
	global_load_dwordx4 v[24:27], v98, s[6:7] offset:768 nt
	global_load_dwordx4 v[28:31], v99, s[6:7] offset:768 nt
.Lcv_ewu_loop:
	s_lshr_b32 s16, s20, 7
	s_lshl_b32 s16, s16, 22
	s_and_b32 s17, s20, 7
	s_lshl_b32 s17, s17, 19
	s_add_u32 s16, s16, s17
	s_bfe_u32 s17, s20, 0x40003
	s_lshl_b32 s17, s17, 7
	s_add_u32 s16, s16, s17
	s_add_u32 s8, s14, s16
	s_addc_u32 s9, s15, 0
	s_waitcnt vmcnt(0)
	ds_write2_b32 v80, v0, v1 offset1:1
	ds_write2_b32 v80, v2, v3 offset0:2 offset1:3
	ds_write2_b32 v81, v4, v5 offset1:1
	ds_write2_b32 v81, v6, v7 offset0:2 offset1:3
	ds_write2_b32 v82, v8, v9 offset1:1
	ds_write2_b32 v82, v10, v11 offset0:2 offset1:3
	ds_write2_b32 v83, v12, v13 offset1:1
	ds_write2_b32 v83, v14, v15 offset0:2 offset1:3
	ds_write2_b32 v84, v16, v17 offset1:1
	ds_write2_b32 v84, v18, v19 offset0:2 offset1:3
	ds_write2_b32 v85, v20, v21 offset1:1
	ds_write2_b32 v85, v22, v23 offset0:2 offset1:3
	ds_write2_b32 v86, v24, v25 offset1:1
	ds_write2_b32 v86, v26, v27 offset0:2 offset1:3
	ds_write2_b32 v87, v28, v29 offset1:1
	ds_write2_b32 v87, v30, v31 offset0:2 offset1:3
	s_add_i32 s21, s20, s59
	s_cmpk_lt_i32 s21, 0x1000
	s_cbranch_scc0 .Lcv_ewu_nopf
	s_lshr_b32 s16, s21, 7
	s_lshl_b32 s16, s16, 23
	s_bfe_u32 s17, s21, 0x40003
	s_lshl_b32 s17, s17, 19
	s_add_u32 s16, s16, s17
	s_and_b32 s17, s21, 7
	s_lshl_b32 s17, s17, 10
	s_add_u32 s16, s16, s17
	s_add_u32 s6, s12, s16
	s_addc_u32 s7, s13, 0
	global_load_dwordx4 v[0:3], v98, s[6:7] nt
	global_load_dwordx4 v[4:7], v99, s[6:7] nt
	global_load_dwordx4 v[8:11], v98, s[6:7] offset:256 nt
	global_load_dwordx4 v[12:15], v99, s[6:7] offset:256 nt
	global_load_dwordx4 v[16:19], v98, s[6:7] offset:512 nt
	global_load_dwordx4 v[20:23], v99, s[6:7] offset:512 nt
	global_load_dwordx4 v[24:27], v98, s[6:7] offset:768 nt
	global_load_dwordx4 v[28:31], v99, s[6:7] offset:768 nt
.Lcv_ewu_nopf:
	s_waitcnt lgkmcnt(0)
	s_barrier
	ds_read2_b32 v[32:33], v88 offset1:65
	ds_read2_b32 v[34:35], v88 offset0:130 offset1:195
	ds_read2_b32 v[36:37], v89 offset0:4 offset1:69
	ds_read2_b32 v[38:39], v89 offset0:134 offset1:199
	ds_read2_b32 v[40:41], v90 offset1:65
	ds_read2_b32 v[42:43], v90 offset0:130 offset1:195
	ds_read2_b32 v[44:45], v91 offset0:4 offset1:69
	ds_read2_b32 v[46:47], v91 offset0:134 offset1:199
	ds_read2_b32 v[48:49], v92 offset1:65
	ds_read2_b32 v[50:51], v92 offset0:130 offset1:195
	ds_read2_b32 v[52:53], v93 offset0:4 offset1:69
	ds_read2_b32 v[54:55], v93 offset0:134 offset1:199
	ds_read2_b32 v[56:57], v94 offset1:65
	ds_read2_b32 v[58:59], v94 offset0:130 offset1:195
	ds_read2_b32 v[60:61], v95 offset0:4 offset1:69
	ds_read2_b32 v[62:63], v95 offset0:134 offset1:199
	s_waitcnt lgkmcnt(12)
	v_cvt_pk_bf16_f32 v64, v32, v33
	v_cvt_pk_bf16_f32 v65, v34, v35
	v_cvt_pk_bf16_f32 v66, v36, v37
	v_cvt_pk_bf16_f32 v67, v38, v39
	global_store_dwordx4 v103, v[64:67], s[8:9]
	s_waitcnt lgkmcnt(8)
	v_cvt_pk_bf16_f32 v68, v40, v41
	v_cvt_pk_bf16_f32 v69, v42, v43
	v_cvt_pk_bf16_f32 v70, v44, v45
	v_cvt_pk_bf16_f32 v71, v46, v47
	s_add_u32 s10, s8, 0x20000
	s_addc_u32 s11, s9, 0
	global_store_dwordx4 v103, v[68:71], s[10:11]
	s_waitcnt lgkmcnt(4)
	v_cvt_pk_bf16_f32 v72, v48, v49
	v_cvt_pk_bf16_f32 v73, v50, v51
	v_cvt_pk_bf16_f32 v74, v52, v53
	v_cvt_pk_bf16_f32 v75, v54, v55
	s_add_u32 s10, s8, 0x40000
	s_addc_u32 s11, s9, 0
	global_store_dwordx4 v103, v[72:75], s[10:11]
	s_waitcnt lgkmcnt(0)
	v_cvt_pk_bf16_f32 v76, v56, v57
	v_cvt_pk_bf16_f32 v77, v58, v59
	v_cvt_pk_bf16_f32 v78, v60, v61
	v_cvt_pk_bf16_f32 v79, v62, v63
	s_add_u32 s10, s8, 0x60000
	s_addc_u32 s11, s9, 0
	global_store_dwordx4 v103, v[76:79], s[10:11]
	s_barrier
	s_mov_b32 s20, s21
	s_cmpk_lt_i32 s20, 0x1000
	s_cbranch_scc1 .Lcv_ewu_loop
